# P0: counted vmcnt(4) at the item top leaves the previous item's four output stores in flight
# speedup vs baseline: 1.0083x; 1.0031x over previous
; __global__ void __launch_bounds__(NTHR, 2) fwd_kernel(Args a) {
;     ...
;           int it = bid; P0Desc dc, dn; f32x4 tv[8];
;           bool have = p0_decode(it, ts, wid, lane, dc); if (have) p0_load(dc, tv);
;           while (have) {
;               p0_to_lds(dc, tv, T, wid, lane);
.Lp0_nogain_a:
	s_waitcnt vmcnt(0)
	s_branch .LBB0_86

; #define LAS __attribute__((address_space(3)))
; __device__ __forceinline__ void p0_to_lds(const P0Desc& d, const f32x4 (&tv)[8], LAS float* T, int wid, int lane) {
; #pragma unroll
;     for (int i = 0; i < 8; ++i) { const float g = d.gk ? d.gk[i] : 1.f; LAS float* tp = T + (wid * 8 + i) * 257 + 4 * lane; tp[0] = tv[i].x * g; tp[1] = tv[i].y * g; tp[2] = tv[i].z * g; tp[3] = tv[i].w * g; }
; }
.LBB0_86:
	s_cmp_lg_u64 s[26:27], 0
	s_cselect_b64 s[36:37], -1, 0
	s_cmp_eq_u64 s[26:27], 0
	s_cbranch_scc1 .LBB0_144
	s_waitcnt vmcnt(4)
	v_mov_b32_e32 v56, v248
	v_mov_b32_e32 v57, v249
	v_pk_mul_f32 v[52:53], v[4:5], v[56:57] op_sel_hi:[1,0]
	v_pk_mul_f32 v[54:55], v[6:7], v[56:57] op_sel_hi:[1,0]
	v_mov_b32_e32 v46, v57
	ds_write_b128 v50, v[52:55]
	s_cbranch_execnz .LBB0_89
.LBB0_88:
	v_mov_b32_e32 v46, 1.0
	s_waitcnt vmcnt(4)
	ds_write_b128 v50, v[4:7]
.LBB0_89:
	s_waitcnt vmcnt(4)
	v_pk_mul_f32 v[52:53], v[0:1], v[46:47] op_sel_hi:[1,0]
	v_add_u32_e32 v51, 0x404, v50
	ds_write2_b32 v51, v52, v53 offset1:1
	v_pk_mul_f32 v[52:53], v[2:3], v[46:47] op_sel_hi:[1,0]
	v_add_u32_e32 v46, 0x40c, v50
	ds_write2_b32 v46, v52, v53 offset1:1
	v_cndmask_b32_e64 v46, 0, 1, s[36:37]
	v_cmp_ne_u32_e64 s[6:7], 1, v46
	s_andn2_b64 vcc, exec, s[36:37]
	v_add_u32_e32 v51, 0x808, v50
	s_cbranch_vccnz .LBB0_145
	s_waitcnt vmcnt(4)
	v_mov_b32_e32 v52, v250
	v_mov_b32_e32 v53, v251
	v_pk_mul_f32 v[54:55], v[8:9], v[52:53] op_sel_hi:[1,0]
	v_pk_mul_f32 v[56:57], v[10:11], v[52:53] op_sel_hi:[1,0]
	v_mov_b32_e32 v46, v53
	ds_write2_b64 v51, v[54:55], v[56:57] offset1:1
	s_cbranch_execnz .LBB0_92

; #define LAS __attribute__((address_space(3)))
; __device__ __forceinline__ void p0_to_lds(const P0Desc& d, const f32x4 (&tv)[8], LAS float* T, int wid, int lane) {
; #pragma unroll
;     for (int i = 0; i < 8; ++i) { const float g = d.gk ? d.gk[i] : 1.f; LAS float* tp = T + (wid * 8 + i) * 257 + 4 * lane; tp[0] = tv[i].x * g; tp[1] = tv[i].y * g; tp[2] = tv[i].z * g; tp[3] = tv[i].w * g; }
; }
.LBB0_92:
	v_pk_mul_f32 v[52:53], v[12:13], v[46:47] op_sel_hi:[1,0]
	v_add_u32_e32 v51, 0xc0c, v50
	ds_write2_b32 v51, v52, v53 offset1:1
	v_pk_mul_f32 v[52:53], v[14:15], v[46:47] op_sel_hi:[1,0]
	v_add_u32_e32 v46, 0xc14, v50
	s_and_b64 vcc, exec, s[6:7]
	ds_write2_b32 v46, v52, v53 offset1:1
	s_cbranch_vccnz .LBB0_146
	s_waitcnt vmcnt(4)
	v_mov_b32_e32 v56, v252
	v_mov_b32_e32 v57, v253
	v_pk_mul_f32 v[52:53], v[16:17], v[56:57] op_sel_hi:[1,0]
	v_pk_mul_f32 v[54:55], v[18:19], v[56:57] op_sel_hi:[1,0]
	v_mov_b32_e32 v46, v57
	ds_write_b128 v50, v[52:55] offset:4112
	s_cbranch_execnz .LBB0_95

; #define LAS __attribute__((address_space(3)))
; __device__ __forceinline__ void p0_to_lds(const P0Desc& d, const f32x4 (&tv)[8], LAS float* T, int wid, int lane) {
; #pragma unroll
;     for (int i = 0; i < 8; ++i) { const float g = d.gk ? d.gk[i] : 1.f; LAS float* tp = T + (wid * 8 + i) * 257 + 4 * lane; tp[0] = tv[i].x * g; tp[1] = tv[i].y * g; tp[2] = tv[i].z * g; tp[3] = tv[i].w * g; }
; }
.LBB0_95:
	v_pk_mul_f32 v[52:53], v[20:21], v[46:47] op_sel_hi:[1,0]
	v_add_u32_e32 v51, 0x1414, v50
	ds_write2_b32 v51, v52, v53 offset1:1
	v_pk_mul_f32 v[52:53], v[22:23], v[46:47] op_sel_hi:[1,0]
	v_add_u32_e32 v46, 0x141c, v50
	s_and_b64 vcc, exec, s[6:7]
	v_add_u32_e32 v51, 0x1818, v50
	ds_write2_b32 v46, v52, v53 offset1:1
	s_cbranch_vccnz .LBB0_147
	s_waitcnt vmcnt(4)
	v_mov_b32_e32 v52, v254
	v_mov_b32_e32 v53, v255
	v_pk_mul_f32 v[54:55], v[28:29], v[52:53] op_sel_hi:[1,0]
	v_pk_mul_f32 v[56:57], v[30:31], v[52:53] op_sel_hi:[1,0]
	v_mov_b32_e32 v46, v53
	ds_write2_b64 v51, v[54:55], v[56:57] offset1:1
	s_cbranch_execnz .LBB0_98
